# v84 with the two SwiGLU K-loop heads padded to byte offset 0 mod 8 instead of 4 (placement comparison, everything else unchanged)
# speedup vs baseline: 1.0097x; 1.0097x over previous
.LBB0_572:
	s_ashr_i32 s15, s14, 31
	s_lshl_b64 s[16:17], s[14:15], 19
	s_add_u32 s16, s36, s16
	s_addc_u32 s17, s37, s17
	s_and_b64 s[18:19], s[2:3], exec
	s_cselect_b32 s15, s17, s29
	s_cselect_b32 s54, s16, s28
	s_ashr_i32 s13, s12, 31
	s_lshl_b64 s[18:19], s[12:13], 19
	s_add_u32 s18, s38, s18
	s_addc_u32 s19, s39, s19
	s_and_b64 s[34:35], s[2:3], exec
	s_cselect_b32 s13, s19, s31
	s_cselect_b32 s55, s18, s30
	s_add_u32 s28, s28, 0x40080
	s_addc_u32 s29, s29, 0
	s_add_u32 s56, s30, 0x100
	v_mov_b32_e32 v0, 0
	s_addc_u32 s57, s31, 0
	s_mov_b32 s58, -2
	v_mov_b32_e32 v1, v0
	v_mov_b32_e32 v2, v0
	v_mov_b32_e32 v3, v0
	v_mov_b32_e32 v8, v0
	v_mov_b32_e32 v9, v0
	v_mov_b32_e32 v10, v0
	v_mov_b32_e32 v11, v0
	v_mov_b32_e32 v16, v0
	v_mov_b32_e32 v17, v0
	v_mov_b32_e32 v18, v0
	v_mov_b32_e32 v19, v0
	v_mov_b32_e32 v24, v0
	v_mov_b32_e32 v25, v0
	v_mov_b32_e32 v26, v0
	v_mov_b32_e32 v27, v0
	v_mov_b32_e32 v32, v0
	v_mov_b32_e32 v33, v0
	v_mov_b32_e32 v34, v0
	v_mov_b32_e32 v35, v0
	v_mov_b32_e32 v40, v0
	v_mov_b32_e32 v41, v0
	v_mov_b32_e32 v42, v0
	v_mov_b32_e32 v43, v0
	v_mov_b32_e32 v48, v0
	v_mov_b32_e32 v49, v0
	v_mov_b32_e32 v50, v0
	v_mov_b32_e32 v51, v0
	v_mov_b32_e32 v56, v0
	v_mov_b32_e32 v57, v0
	v_mov_b32_e32 v58, v0
	v_mov_b32_e32 v59, v0
	v_mov_b32_e32 v4, v0
	v_mov_b32_e32 v5, v0
	v_mov_b32_e32 v6, v0
	v_mov_b32_e32 v7, v0
	v_mov_b32_e32 v12, v0
	v_mov_b32_e32 v13, v0
	v_mov_b32_e32 v14, v0
	v_mov_b32_e32 v15, v0
	v_mov_b32_e32 v20, v0
	v_mov_b32_e32 v21, v0
	v_mov_b32_e32 v22, v0
	v_mov_b32_e32 v23, v0
	v_mov_b32_e32 v28, v0
	v_mov_b32_e32 v29, v0
	v_mov_b32_e32 v30, v0
	v_mov_b32_e32 v31, v0
	v_mov_b32_e32 v36, v0
	v_mov_b32_e32 v37, v0
	v_mov_b32_e32 v38, v0
	v_mov_b32_e32 v39, v0
	v_mov_b32_e32 v44, v0
	v_mov_b32_e32 v45, v0
	v_mov_b32_e32 v46, v0
	v_mov_b32_e32 v47, v0
	v_mov_b32_e32 v52, v0
	v_mov_b32_e32 v53, v0
	v_mov_b32_e32 v54, v0
	v_mov_b32_e32 v55, v0
	v_mov_b32_e32 v60, v0
	v_mov_b32_e32 v61, v0
	v_mov_b32_e32 v62, v0
	v_mov_b32_e32 v63, v0
	v_mov_b32_e32 v64, v0
	v_mov_b32_e32 v65, v0
	v_mov_b32_e32 v66, v0
	v_mov_b32_e32 v67, v0
	v_mov_b32_e32 v72, v0
	v_mov_b32_e32 v73, v0
	v_mov_b32_e32 v74, v0
	v_mov_b32_e32 v75, v0
	v_mov_b32_e32 v80, v0
	v_mov_b32_e32 v81, v0
	v_mov_b32_e32 v82, v0
	v_mov_b32_e32 v83, v0
	v_mov_b32_e32 v88, v0
	v_mov_b32_e32 v89, v0
	v_mov_b32_e32 v90, v0
	v_mov_b32_e32 v91, v0
	v_mov_b32_e32 v96, v0
	v_mov_b32_e32 v97, v0
	v_mov_b32_e32 v98, v0
	v_mov_b32_e32 v99, v0
	v_mov_b32_e32 v104, v0
	v_mov_b32_e32 v105, v0
	v_mov_b32_e32 v106, v0
	v_mov_b32_e32 v107, v0
	v_mov_b32_e32 v112, v0
	v_mov_b32_e32 v113, v0
	v_mov_b32_e32 v114, v0
	v_mov_b32_e32 v115, v0
	v_mov_b32_e32 v120, v0
	v_mov_b32_e32 v121, v0
	v_mov_b32_e32 v122, v0
	v_mov_b32_e32 v123, v0
	v_mov_b32_e32 v68, v0
	v_mov_b32_e32 v69, v0
	v_mov_b32_e32 v70, v0
	v_mov_b32_e32 v71, v0
	v_mov_b32_e32 v76, v0
	v_mov_b32_e32 v77, v0
	v_mov_b32_e32 v78, v0
	v_mov_b32_e32 v79, v0
	v_mov_b32_e32 v84, v0
	v_mov_b32_e32 v85, v0
	v_mov_b32_e32 v86, v0
	v_mov_b32_e32 v87, v0
	v_mov_b32_e32 v92, v0
	v_mov_b32_e32 v93, v0
	v_mov_b32_e32 v94, v0
	v_mov_b32_e32 v95, v0
	v_mov_b32_e32 v100, v0
	v_mov_b32_e32 v101, v0
	v_mov_b32_e32 v102, v0
	v_mov_b32_e32 v103, v0
	v_mov_b32_e32 v108, v0
	v_mov_b32_e32 v109, v0
	v_mov_b32_e32 v110, v0
	v_mov_b32_e32 v111, v0
	v_mov_b32_e32 v116, v0
	v_mov_b32_e32 v117, v0
	v_mov_b32_e32 v118, v0
	v_mov_b32_e32 v119, v0
	v_mov_b32_e32 v124, v0
	v_mov_b32_e32 v125, v0
	v_mov_b32_e32 v126, v0
	v_mov_b32_e32 v127, v0
	s_nop 0

.LBB0_647:
	s_add_u32 s55, s16, 0x100
	v_mov_b32_e32 v0, 0
	s_addc_u32 s56, s17, 0
	s_mov_b32 s57, -2
	v_mov_b32_e32 v1, v0
	v_mov_b32_e32 v2, v0
	v_mov_b32_e32 v3, v0
	v_mov_b32_e32 v4, v0
	v_mov_b32_e32 v5, v0
	v_mov_b32_e32 v6, v0
	v_mov_b32_e32 v7, v0
	v_mov_b32_e32 v16, v0
	v_mov_b32_e32 v17, v0
	v_mov_b32_e32 v18, v0
	v_mov_b32_e32 v19, v0
	v_mov_b32_e32 v20, v0
	v_mov_b32_e32 v21, v0
	v_mov_b32_e32 v22, v0
	v_mov_b32_e32 v23, v0
	v_mov_b32_e32 v32, v0
	v_mov_b32_e32 v33, v0
	v_mov_b32_e32 v34, v0
	v_mov_b32_e32 v35, v0
	v_mov_b32_e32 v36, v0
	v_mov_b32_e32 v37, v0
	v_mov_b32_e32 v38, v0
	v_mov_b32_e32 v39, v0
	v_mov_b32_e32 v48, v0
	v_mov_b32_e32 v49, v0
	v_mov_b32_e32 v50, v0
	v_mov_b32_e32 v51, v0
	v_mov_b32_e32 v52, v0
	v_mov_b32_e32 v53, v0
	v_mov_b32_e32 v54, v0
	v_mov_b32_e32 v55, v0
	v_mov_b32_e32 v8, v0
	v_mov_b32_e32 v9, v0
	v_mov_b32_e32 v10, v0
	v_mov_b32_e32 v11, v0
	v_mov_b32_e32 v12, v0
	v_mov_b32_e32 v13, v0
	v_mov_b32_e32 v14, v0
	v_mov_b32_e32 v15, v0
	v_mov_b32_e32 v24, v0
	v_mov_b32_e32 v25, v0
	v_mov_b32_e32 v26, v0
	v_mov_b32_e32 v27, v0
	v_mov_b32_e32 v28, v0
	v_mov_b32_e32 v29, v0
	v_mov_b32_e32 v30, v0
	v_mov_b32_e32 v31, v0
	v_mov_b32_e32 v40, v0
	v_mov_b32_e32 v41, v0
	v_mov_b32_e32 v42, v0
	v_mov_b32_e32 v43, v0
	v_mov_b32_e32 v44, v0
	v_mov_b32_e32 v45, v0
	v_mov_b32_e32 v46, v0
	v_mov_b32_e32 v47, v0
	v_mov_b32_e32 v56, v0
	v_mov_b32_e32 v57, v0
	v_mov_b32_e32 v58, v0
	v_mov_b32_e32 v59, v0
	v_mov_b32_e32 v60, v0
	v_mov_b32_e32 v61, v0
	v_mov_b32_e32 v62, v0
	v_mov_b32_e32 v63, v0
	v_mov_b32_e32 v64, v0
	v_mov_b32_e32 v65, v0
	v_mov_b32_e32 v66, v0
	v_mov_b32_e32 v67, v0
	v_mov_b32_e32 v68, v0
	v_mov_b32_e32 v69, v0
	v_mov_b32_e32 v70, v0
	v_mov_b32_e32 v71, v0
	v_mov_b32_e32 v80, v0
	v_mov_b32_e32 v81, v0
	v_mov_b32_e32 v82, v0
	v_mov_b32_e32 v83, v0
	v_mov_b32_e32 v84, v0
	v_mov_b32_e32 v85, v0
	v_mov_b32_e32 v86, v0
	v_mov_b32_e32 v87, v0
	v_mov_b32_e32 v96, v0
	v_mov_b32_e32 v97, v0
	v_mov_b32_e32 v98, v0
	v_mov_b32_e32 v99, v0
	v_mov_b32_e32 v100, v0
	v_mov_b32_e32 v101, v0
	v_mov_b32_e32 v102, v0
	v_mov_b32_e32 v103, v0
	v_mov_b32_e32 v104, v0
	v_mov_b32_e32 v105, v0
	v_mov_b32_e32 v106, v0
	v_mov_b32_e32 v107, v0
	v_mov_b32_e32 v108, v0
	v_mov_b32_e32 v109, v0
	v_mov_b32_e32 v110, v0
	v_mov_b32_e32 v111, v0
	v_mov_b32_e32 v72, v0
	v_mov_b32_e32 v73, v0
	v_mov_b32_e32 v74, v0
	v_mov_b32_e32 v75, v0
	v_mov_b32_e32 v76, v0
	v_mov_b32_e32 v77, v0
	v_mov_b32_e32 v78, v0
	v_mov_b32_e32 v79, v0
	v_mov_b32_e32 v88, v0
	v_mov_b32_e32 v89, v0
	v_mov_b32_e32 v90, v0
	v_mov_b32_e32 v91, v0
	v_mov_b32_e32 v92, v0
	v_mov_b32_e32 v93, v0
	v_mov_b32_e32 v94, v0
	v_mov_b32_e32 v95, v0
	v_mov_b32_e32 v112, v0
	v_mov_b32_e32 v113, v0
	v_mov_b32_e32 v114, v0
	v_mov_b32_e32 v115, v0
	v_mov_b32_e32 v116, v0
	v_mov_b32_e32 v117, v0
	v_mov_b32_e32 v118, v0
	v_mov_b32_e32 v119, v0
	v_mov_b32_e32 v120, v0
	v_mov_b32_e32 v121, v0
	v_mov_b32_e32 v122, v0
	v_mov_b32_e32 v123, v0
	v_mov_b32_e32 v124, v0
	v_mov_b32_e32 v125, v0
	v_mov_b32_e32 v126, v0
	v_mov_b32_e32 v127, v0
	s_nop 0
	s_nop 0

.LBB0_1307:
	s_ashr_i32 s15, s14, 31
	s_lshl_b64 s[16:17], s[14:15], 19
	s_add_u32 s16, s30, s16
	s_addc_u32 s17, s31, s17
	s_and_b64 s[18:19], s[2:3], exec
	s_cselect_b32 s15, s17, s23
	s_cselect_b32 s50, s16, s22
	s_ashr_i32 s13, s12, 31
	s_lshl_b64 s[18:19], s[12:13], 19
	s_add_u32 s18, s34, s18
	s_addc_u32 s19, s35, s19
	s_and_b64 s[28:29], s[2:3], exec
	s_cselect_b32 s13, s19, s25
	s_cselect_b32 s51, s18, s24
	s_add_u32 s22, s22, 0x40080
	s_addc_u32 s23, s23, 0
	s_add_u32 s52, s24, 0x100
	v_mov_b32_e32 v0, 0
	s_addc_u32 s53, s25, 0
	s_mov_b32 s54, -2
	v_mov_b32_e32 v1, v0
	v_mov_b32_e32 v2, v0
	v_mov_b32_e32 v3, v0
	v_mov_b32_e32 v8, v0
	v_mov_b32_e32 v9, v0
	v_mov_b32_e32 v10, v0
	v_mov_b32_e32 v11, v0
	v_mov_b32_e32 v16, v0
	v_mov_b32_e32 v17, v0
	v_mov_b32_e32 v18, v0
	v_mov_b32_e32 v19, v0
	v_mov_b32_e32 v24, v0
	v_mov_b32_e32 v25, v0
	v_mov_b32_e32 v26, v0
	v_mov_b32_e32 v27, v0
	v_mov_b32_e32 v32, v0
	v_mov_b32_e32 v33, v0
	v_mov_b32_e32 v34, v0
	v_mov_b32_e32 v35, v0
	v_mov_b32_e32 v40, v0
	v_mov_b32_e32 v41, v0
	v_mov_b32_e32 v42, v0
	v_mov_b32_e32 v43, v0
	v_mov_b32_e32 v48, v0
	v_mov_b32_e32 v49, v0
	v_mov_b32_e32 v50, v0
	v_mov_b32_e32 v51, v0
	v_mov_b32_e32 v56, v0
	v_mov_b32_e32 v57, v0
	v_mov_b32_e32 v58, v0
	v_mov_b32_e32 v59, v0
	v_mov_b32_e32 v4, v0
	v_mov_b32_e32 v5, v0
	v_mov_b32_e32 v6, v0
	v_mov_b32_e32 v7, v0
	v_mov_b32_e32 v12, v0
	v_mov_b32_e32 v13, v0
	v_mov_b32_e32 v14, v0
	v_mov_b32_e32 v15, v0
	v_mov_b32_e32 v20, v0
	v_mov_b32_e32 v21, v0
	v_mov_b32_e32 v22, v0
	v_mov_b32_e32 v23, v0
	v_mov_b32_e32 v28, v0
	v_mov_b32_e32 v29, v0
	v_mov_b32_e32 v30, v0
	v_mov_b32_e32 v31, v0
	v_mov_b32_e32 v36, v0
	v_mov_b32_e32 v37, v0
	v_mov_b32_e32 v38, v0
	v_mov_b32_e32 v39, v0
	v_mov_b32_e32 v44, v0
	v_mov_b32_e32 v45, v0
	v_mov_b32_e32 v46, v0
	v_mov_b32_e32 v47, v0
	v_mov_b32_e32 v52, v0
	v_mov_b32_e32 v53, v0
	v_mov_b32_e32 v54, v0
	v_mov_b32_e32 v55, v0
	v_mov_b32_e32 v60, v0
	v_mov_b32_e32 v61, v0
	v_mov_b32_e32 v62, v0
	v_mov_b32_e32 v63, v0
	v_mov_b32_e32 v64, v0
	v_mov_b32_e32 v65, v0
	v_mov_b32_e32 v66, v0
	v_mov_b32_e32 v67, v0
	v_mov_b32_e32 v72, v0
	v_mov_b32_e32 v73, v0
	v_mov_b32_e32 v74, v0
	v_mov_b32_e32 v75, v0
	v_mov_b32_e32 v80, v0
	v_mov_b32_e32 v81, v0
	v_mov_b32_e32 v82, v0
	v_mov_b32_e32 v83, v0
	v_mov_b32_e32 v88, v0
	v_mov_b32_e32 v89, v0
	v_mov_b32_e32 v90, v0
	v_mov_b32_e32 v91, v0
	v_mov_b32_e32 v96, v0
	v_mov_b32_e32 v97, v0
	v_mov_b32_e32 v98, v0
	v_mov_b32_e32 v99, v0
	v_mov_b32_e32 v104, v0
	v_mov_b32_e32 v105, v0
	v_mov_b32_e32 v106, v0
	v_mov_b32_e32 v107, v0
	v_mov_b32_e32 v112, v0
	v_mov_b32_e32 v113, v0
	v_mov_b32_e32 v114, v0
	v_mov_b32_e32 v115, v0
	v_mov_b32_e32 v120, v0
	v_mov_b32_e32 v121, v0
	v_mov_b32_e32 v122, v0
	v_mov_b32_e32 v123, v0
	v_mov_b32_e32 v68, v0
	v_mov_b32_e32 v69, v0
	v_mov_b32_e32 v70, v0
	v_mov_b32_e32 v71, v0
	v_mov_b32_e32 v76, v0
	v_mov_b32_e32 v77, v0
	v_mov_b32_e32 v78, v0
	v_mov_b32_e32 v79, v0
	v_mov_b32_e32 v84, v0
	v_mov_b32_e32 v85, v0
	v_mov_b32_e32 v86, v0
	v_mov_b32_e32 v87, v0
	v_mov_b32_e32 v92, v0
	v_mov_b32_e32 v93, v0
	v_mov_b32_e32 v94, v0
	v_mov_b32_e32 v95, v0
	v_mov_b32_e32 v100, v0
	v_mov_b32_e32 v101, v0
	v_mov_b32_e32 v102, v0
	v_mov_b32_e32 v103, v0
	v_mov_b32_e32 v108, v0
	v_mov_b32_e32 v109, v0
	v_mov_b32_e32 v110, v0
	v_mov_b32_e32 v111, v0
	v_mov_b32_e32 v116, v0
	v_mov_b32_e32 v117, v0
	v_mov_b32_e32 v118, v0
	v_mov_b32_e32 v119, v0
	v_mov_b32_e32 v124, v0
	v_mov_b32_e32 v125, v0
	v_mov_b32_e32 v126, v0
	v_mov_b32_e32 v127, v0
	s_nop 0
	s_nop 0

.LBB0_1390:
	s_add_u32 s47, s14, 0x100
	v_mov_b32_e32 v0, 0
	s_addc_u32 s48, s15, 0
	s_mov_b32 s49, -2
	v_mov_b32_e32 v1, v0
	v_mov_b32_e32 v2, v0
	v_mov_b32_e32 v3, v0
	v_mov_b32_e32 v4, v0
	v_mov_b32_e32 v5, v0
	v_mov_b32_e32 v6, v0
	v_mov_b32_e32 v7, v0
	v_mov_b32_e32 v12, v0
	v_mov_b32_e32 v13, v0
	v_mov_b32_e32 v14, v0
	v_mov_b32_e32 v15, v0
	v_mov_b32_e32 v20, v0
	v_mov_b32_e32 v21, v0
	v_mov_b32_e32 v22, v0
	v_mov_b32_e32 v23, v0
	v_mov_b32_e32 v28, v0
	v_mov_b32_e32 v29, v0
	v_mov_b32_e32 v30, v0
	v_mov_b32_e32 v31, v0
	v_mov_b32_e32 v36, v0
	v_mov_b32_e32 v37, v0
	v_mov_b32_e32 v38, v0
	v_mov_b32_e32 v39, v0
	v_mov_b32_e32 v44, v0
	v_mov_b32_e32 v45, v0
	v_mov_b32_e32 v46, v0
	v_mov_b32_e32 v47, v0
	v_mov_b32_e32 v52, v0
	v_mov_b32_e32 v53, v0
	v_mov_b32_e32 v54, v0
	v_mov_b32_e32 v55, v0
	v_mov_b32_e32 v8, v0
	v_mov_b32_e32 v9, v0
	v_mov_b32_e32 v10, v0
	v_mov_b32_e32 v11, v0
	v_mov_b32_e32 v16, v0
	v_mov_b32_e32 v17, v0
	v_mov_b32_e32 v18, v0
	v_mov_b32_e32 v19, v0
	v_mov_b32_e32 v24, v0
	v_mov_b32_e32 v25, v0
	v_mov_b32_e32 v26, v0
	v_mov_b32_e32 v27, v0
	v_mov_b32_e32 v32, v0
	v_mov_b32_e32 v33, v0
	v_mov_b32_e32 v34, v0
	v_mov_b32_e32 v35, v0
	v_mov_b32_e32 v40, v0
	v_mov_b32_e32 v41, v0
	v_mov_b32_e32 v42, v0
	v_mov_b32_e32 v43, v0
	v_mov_b32_e32 v48, v0
	v_mov_b32_e32 v49, v0
	v_mov_b32_e32 v50, v0
	v_mov_b32_e32 v51, v0
	v_mov_b32_e32 v56, v0
	v_mov_b32_e32 v57, v0
	v_mov_b32_e32 v58, v0
	v_mov_b32_e32 v59, v0
	v_mov_b32_e32 v60, v0
	v_mov_b32_e32 v61, v0
	v_mov_b32_e32 v62, v0
	v_mov_b32_e32 v63, v0
	v_mov_b32_e32 v64, v0
	v_mov_b32_e32 v65, v0
	v_mov_b32_e32 v66, v0
	v_mov_b32_e32 v67, v0
	v_mov_b32_e32 v68, v0
	v_mov_b32_e32 v69, v0
	v_mov_b32_e32 v70, v0
	v_mov_b32_e32 v71, v0
	v_mov_b32_e32 v76, v0
	v_mov_b32_e32 v77, v0
	v_mov_b32_e32 v78, v0
	v_mov_b32_e32 v79, v0
	v_mov_b32_e32 v84, v0
	v_mov_b32_e32 v85, v0
	v_mov_b32_e32 v86, v0
	v_mov_b32_e32 v87, v0
	v_mov_b32_e32 v96, v0
	v_mov_b32_e32 v97, v0
	v_mov_b32_e32 v98, v0
	v_mov_b32_e32 v99, v0
	v_mov_b32_e32 v100, v0
	v_mov_b32_e32 v101, v0
	v_mov_b32_e32 v102, v0
	v_mov_b32_e32 v103, v0
	v_mov_b32_e32 v104, v0
	v_mov_b32_e32 v105, v0
	v_mov_b32_e32 v106, v0
	v_mov_b32_e32 v107, v0
	v_mov_b32_e32 v108, v0
	v_mov_b32_e32 v109, v0
	v_mov_b32_e32 v110, v0
	v_mov_b32_e32 v111, v0
	v_mov_b32_e32 v72, v0
	v_mov_b32_e32 v73, v0
	v_mov_b32_e32 v74, v0
	v_mov_b32_e32 v75, v0
	v_mov_b32_e32 v80, v0
	v_mov_b32_e32 v81, v0
	v_mov_b32_e32 v82, v0
	v_mov_b32_e32 v83, v0
	v_mov_b32_e32 v88, v0
	v_mov_b32_e32 v89, v0
	v_mov_b32_e32 v90, v0
	v_mov_b32_e32 v91, v0
	v_mov_b32_e32 v92, v0
	v_mov_b32_e32 v93, v0
	v_mov_b32_e32 v94, v0
	v_mov_b32_e32 v95, v0
	v_mov_b32_e32 v112, v0
	v_mov_b32_e32 v113, v0
	v_mov_b32_e32 v114, v0
	v_mov_b32_e32 v115, v0
	v_mov_b32_e32 v116, v0
	v_mov_b32_e32 v117, v0
	v_mov_b32_e32 v118, v0
	v_mov_b32_e32 v119, v0
	v_mov_b32_e32 v120, v0
	v_mov_b32_e32 v121, v0
	v_mov_b32_e32 v122, v0
	v_mov_b32_e32 v123, v0
	v_mov_b32_e32 v124, v0
	v_mov_b32_e32 v125, v0
	v_mov_b32_e32 v126, v0
	v_mov_b32_e32 v127, v0
	s_nop 0
